# v26 + P13 (S5 output GEMM) unit order changed so the 4 groups that share each 128-byte line of the output run concurrently on adjacent workgroups of one XCD
# speedup vs baseline: 1.0027x; 1.0016x over previous
; #define PG8_STAGE(bufoff, gbase, voff) do { _Pragma("unroll") for (int _i = 0; _i < 2; ++_i) \
;         __builtin_amdgcn_global_load_lds((const unsigned*)((const char*)(gbase) + (voff)[_i]), (PG8_LAS unsigned*)(lds + (bufoff) + ldsw + _i * 8192), 16, 0, 0); } while (0)
; #define PG8_WAIT_V(n) asm volatile("s_waitcnt vmcnt(" #n ")" ::: "memory")
; #define PG8_BAR __builtin_amdgcn_s_barrier()
; template <class Epi, class Sched, bool ALIGN_EPI = false, bool SP2 = false>
; __device__ __forceinline__ void gemm_phase(PG8_LAS unsigned char* lds, const Gemm g, const Sched& S, const Epi& E) {
;     ...
;     const char* cA = (const char*)g.A + (size_t)cur.pm * tstepA; const char* cB = (const char*)g.Bt + (size_t)cur.pn * tstepB;
;     S.a_ready(cur);
;     if constexpr (SP2) {
;         PG8_STAGE(PG8_SB(0, 0), cB, voffB); PG8_STAGE(PG8_SB(0, 1), cB + hstepB, voffB); PG8_STAGE(PG8_SA(0, 0), cA, voffA); PG8_STAGE(PG8_SA(0, 1), cA + hstepA, voffA);
;         if (wr == 1) PG8_BAR;
;         PG8_WAIT_V(2); PG8_BAR;
;         PG8_STAGE(PG8_SB(1, 0), cB + kstep, voffB); PG8_STAGE(PG8_SA(1, 0), cA + kstep, voffA); PG8_STAGE(PG8_SB(1, 1), cB + hstepB + kstep, voffB);
;         PG8_WAIT_V(6); PG8_BAR;
;     } else {
;         PG8_STAGE(PG8_SB(0, 0), cB, voffB); PG8_STAGE(PG8_SA(0, 0), cA, voffA); PG8_STAGE(PG8_SB(0, 1), cB + hstepB, voffB); PG8_STAGE(PG8_SA(0, 1), cA + hstepA, voffA);
;     __device__ bool next(int i, pg8::Unit& u) const { const long L0 = (long)i * G + c; if (L0 >= total) return false;
;         const int L = (int)(L0 % 8) * (total / 8) + (int)(L0 / 8);
;         const int g = L / per, r = L % per;
;         u.pm = g * nMg + r % nMg; u.pn = g * nNg + r / nMg; return true; }
.LBB0_1276:
	s_cmp_gt_i32 s74, 13
	s_cselect_b64 s[0:1], -1, 0
	s_cmp_lt_i32 s75, 14
	s_cselect_b64 s[2:3], -1, 0
	s_or_b64 s[0:1], s[0:1], s[2:3]
	s_and_b64 vcc, exec, s[0:1]
	s_cbranch_vccnz .LBB0_1347
	s_load_dword s22, s[76:77], 0x190
	s_add_u32 s8, s76, 0x190
	s_addc_u32 s9, s77, 0
	s_cmpk_gt_i32 s70, 0x4ff
	v_readfirstlane_b32 s5, v0
	s_cbranch_scc1 .LBB0_1297
	s_waitcnt vmcnt(0)
	v_lshrrev_b32_e32 v1, 5, v0
	v_lshrrev_b32_e32 v12, 1, v0
	v_and_b32_e32 v1, 4, v1
	v_bfe_u32 v2, v0, 2, 2
	v_and_b32_e32 v10, 24, v12
	v_or3_b32 v1, v1, v2, v10
	v_lshlrev_b32_e32 v2, 4, v0
	v_bfe_u32 v3, v0, 3, 25
	v_and_b32_e32 v5, 32, v0
	v_or_b32_e32 v3, 64, v3
	s_movk_i32 s0, 0x60
	v_bitop3_b32 v11, v2, v5, 48 bitop3:0x6c
	v_and_b32_e32 v13, 64, v0
	v_and_or_b32 v4, v3, s0, v1
	v_or_b32_e32 v2, v11, v13
	v_mul_u32_u24_e32 v4, 0x300, v4
	v_lshrrev_b32_e32 v2, 1, v2
	v_or_b32_e32 v4, v4, v2
	v_lshlrev_b32_e32 v130, 1, v4
	v_bfe_u32 v4, v0, 2, 4
	s_movk_i32 s0, 0x70
	s_ashr_i32 s24, s70, 31
	v_and_or_b32 v3, v3, s0, v4
	s_lshr_b32 s0, s24, 29
	s_add_i32 s0, s70, s0
	s_ashr_i32 s0, s0, 3
	s_mul_i32 s1, s70, 0xa0
	s_mulk_i32 s0, 0xfb01
	s_add_i32 s0, s0, s1
	s_mul_hi_i32 s1, s0, 0x66666667
	s_lshr_b32 s2, s1, 31
	s_ashr_i32 s1, s1, 4
	s_add_i32 s1, s1, s2
	s_mul_i32 s2, s1, 40
	s_sub_i32 s0, s0, s2
	s_and_b32 s2, s0, 3
	s_lshl_b32 s1, s1, 2
	s_add_i32 s1, s1, s2
	s_lshr_b32 s0, s0, 2
	s_bfe_i32 s3, s0, 0x80000
	s_mulk_i32 s3, 0x67
	s_sext_i32_i16 s7, s3
	s_ashr_i32 s7, s7, 9
	s_bfe_u32 s3, s3, 0x1000f
	s_add_i32 s3, s7, s3
	s_mul_i32 s7, s3, 5
	s_sub_i32 s0, s0, s7
	v_mul_u32_u24_e32 v14, 0x300, v3
	s_mul_i32 s2, s1, 5
	s_sext_i32_i8 s0, s0
	v_or_b32_e32 v3, v14, v2
	s_add_i32 s38, s2, s0
	s_lshl_b32 s0, s1, 1
	s_sext_i32_i16 s1, s3
	s_lshr_b32 s6, s5, 6
	v_lshlrev_b32_e32 v132, 1, v3
	v_lshrrev_b32_e32 v3, 3, v0
	s_add_i32 s39, s0, s1
	s_lshr_b32 s4, s5, 8
	s_lshl_b32 s23, s6, 10
	v_and_or_b32 v1, v3, 32, v1
	s_mul_i32 s1, s39, 0x60000
	v_mul_u32_u24_e32 v1, 0x300, v1
	s_mul_hi_i32 s0, s39, 0x60000
	s_add_u32 s2, s80, s1
	v_or_b32_e32 v1, v1, v2
	s_addc_u32 s3, s81, s0
	s_add_i32 s25, s23, 0
	v_lshlrev_b32_e32 v134, 1, v1
	s_add_i32 m0, s25, 0x10000
	v_and_or_b32 v1, v3, 48, v4
	global_load_lds_dwordx4 v134, s[2:3]
	s_add_i32 m0, s25, 0x12000
	s_add_u32 s0, s2, 0x30000
	global_load_lds_dwordx4 v130, s[2:3]
	s_addc_u32 s1, s3, 0
	s_add_i32 m0, s25, 0x14000
	s_mul_i32 s10, s38, 0x60000
	global_load_lds_dwordx4 v134, s[0:1]
	s_add_i32 m0, s25, 0x16000
	v_mul_u32_u24_e32 v15, 0x300, v1
	s_mul_hi_i32 s7, s38, 0x60000
	global_load_lds_dwordx4 v130, s[0:1]
	s_add_u32 s0, s84, s10
	v_or_b32_e32 v1, v2, v15
	s_addc_u32 s1, s85, s7
	s_add_i32 s26, s25, 0x2000
	v_lshlrev_b32_e32 v136, 1, v1
	s_mov_b32 m0, s25
	s_add_u32 s10, s0, 0x30000
	global_load_lds_dwordx4 v136, s[0:1]
	s_mov_b32 m0, s26
	s_addc_u32 s11, s1, 0
	s_add_i32 s27, s25, 0x4000
	global_load_lds_dwordx4 v132, s[0:1]
	s_mov_b32 m0, s27
	s_add_i32 s28, s25, 0x6000
	global_load_lds_dwordx4 v136, s[10:11]
	s_mov_b32 m0, s28
	v_mov_b32_e32 v139, 0
	global_load_lds_dwordx4 v132, s[10:11]
	v_mov_b32_e32 v135, v139
	v_mov_b32_e32 v131, v139
	v_mov_b32_e32 v137, v139
	v_mov_b32_e32 v133, v139
	s_cmp_eq_u32 s4, 1
	s_mov_b32 s29, 0
	v_lshl_add_u64 v[8:9], s[2:3], 0, v[134:135]
	v_lshl_add_u64 v[6:7], s[2:3], 0, v[130:131]
	v_lshl_add_u64 v[2:3], s[0:1], 0, v[136:137]
	s_cselect_b64 s[10:11], -1, 0
	s_cmp_lg_u32 s4, 1
	v_lshl_add_u64 v[4:5], s[0:1], 0, v[132:133]
	s_cbranch_scc1 .LBB0_1280
	s_barrier

; template <class Epi, class Sched, bool ALIGN_EPI = false, bool SP2 = false>
; __device__ __forceinline__ void gemm_phase(PG8_LAS unsigned char* lds, const Gemm g, const Sched& S, const Epi& E) {
;     ...
;         const bool has_next = S.next(ui + 1, nxt);
;         const char* nA = has_next ? (const char*)g.A + (size_t)nxt.pm * tstepA : cA; const char* nB = has_next ? (const char*)g.Bt + (size_t)nxt.pn * tstepB : cB;
;     __device__ bool next(int i, pg8::Unit& u) const { const long L0 = (long)i * G + c; if (L0 >= total) return false;
;         const int L = (int)(L0 % 8) * (total / 8) + (int)(L0 / 8);
;         const int g = L / per, r = L % per;
;         u.pm = g * nMg + r % nMg; u.pn = g * nNg + r / nMg; return true; }
.LBB0_1283:
	s_add_i32 s29, s29, 1
	s_mul_i32 s4, s29, s33
	s_mul_hi_u32 s5, s29, s22
	s_add_i32 s5, s5, s4
	s_mul_i32 s4, s29, s22
	s_add_u32 s4, s4, s70
	s_addc_u32 s5, s5, s24
	v_cmp_gt_i64_e32 vcc, s[4:5], v[146:147]
	v_cmp_lt_i64_e64 s[6:7], s[4:5], v[144:145]
	s_cbranch_vccnz .LBB0_1285
	s_ashr_i32 s16, s5, 31
	s_lshr_b32 s16, s16, 29
	s_add_u32 s16, s4, s16
	s_addc_u32 s17, s5, 0
	s_lshr_b64 s[16:17], s[16:17], 3
	s_lshl_b32 s5, s16, 3
	s_sub_i32 s4, s4, s5
	s_mulk_i32 s4, 0xa0
	s_add_i32 s4, s4, s16
	s_mul_hi_i32 s5, s4, 0x66666667
	s_lshr_b32 s16, s5, 31
	s_ashr_i32 s5, s5, 4
	s_add_i32 s5, s5, s16
	s_mul_i32 s16, s5, 40
	s_sub_i32 s4, s4, s16
	s_and_b32 s16, s4, 3
	s_lshl_b32 s5, s5, 2
	s_add_i32 s5, s5, s16
	s_lshr_b32 s4, s4, 2
	s_mul_i32 s17, s4, 0x67
	s_sext_i32_i16 s20, s17
	s_ashr_i32 s20, s20, 9
	s_bfe_u32 s17, s17, 0x1000f
	s_add_i32 s17, s20, s17
	s_mul_i32 s20, s17, 5
	s_sub_i32 s4, s4, s20
	s_mul_i32 s16, s5, 5
	s_sext_i32_i8 s4, s4
	s_add_i32 s36, s16, s4
	s_lshl_b32 s4, s5, 1
	s_sext_i32_i16 s5, s17
	s_add_i32 s37, s4, s5
